# v84 + K/V staging loads addressed as uniform SGPR base + 32-bit lane offset (two 64-bit VALU adds per step removed)
# speedup vs baseline: 1.0072x; 1.0020x over previous
; __device__ __forceinline__ void attn_unit_pp(int b, int h, int qb, int par, const bf16_t* __restrict__ QBp, const bf16_t* __restrict__ KBp, const bf16_t* __restrict__ VBp, ...
;     ...
;   int woff[4];
; #pragma unroll
;   for (int i = 0; i < 4; ++i) { const int row = sr + 16 * i; woff[i] = g ? (int)(2 * SHM_V) + KSWZ(row, sc * 2) : v_st(row, sc); }
;   const bf16_t* Tsrc = (g ? Kh : Vh) + (long)sr * LD + sc;
;   const char* Kmine = K_lds + g * 128;
;   const int vb0 = (int)(uintptr_t)V_lds + v_rd_base(lane);
;   float m_reg = 0.f, l_reg = 0.f, alpha = 1.f; f32x16 o[4]; f32x16 negm = f32x16{}; f32x16 p0, p1; bf16x8 pa0, pa1, pa2, pa3; bf16x8 stg[4];
; #pragma unroll
;   for (int d = 0; d < 4; ++d) o[d] = f32x16{};
;   constexpr int NT = SEQ / KVBLK;
;   float qn = 0.f;
; #pragma unroll
;   for (int d0 = 0; d0 < 4; ++d0) { const u32x4 w = __builtin_bit_cast(u32x4, qr[d0]);
; #pragma unroll
;     for (int e = 0; e < 4; ++e) { const float lo = __uint_as_float(w[e] << 16), hh = __uint_as_float(w[e] & 0xffff0000u); qn = fmaf(lo, lo, qn); qn = fmaf(hh, hh, qn); } }
;   { auto rr = __builtin_amdgcn_permlane32_swap(__float_as_uint(qn), __float_as_uint(qn), false, false); qn = __uint_as_float(rr[0]) + __uint_as_float(rr[1]); }
;   float sii = 0.f;
;   { const bf16_t* Kw = Kh + (size_t)(q0 + w4 * QBLK + r32) * LD + g * 64 + hi * 8;
; #pragma unroll
;     for (int d0 = 0; d0 < 4; ++d0) { const u32x4 wq = __builtin_bit_cast(u32x4, qr[d0]); const u32x4 wk = __builtin_bit_cast(u32x4, ld8(Kw + d0 * 16));
; #pragma unroll
;       for (int e = 0; e < 4; ++e) { sii = fmaf(__uint_as_float(wq[e] << 16), __uint_as_float(wk[e] << 16), sii); sii = fmaf(__uint_as_float(wq[e] & 0xffff0000u), __uint_as_float(wk[e] & 0xffff0000u), sii); } } }
;   { auto rr = __builtin_amdgcn_permlane32_swap(__float_as_uint(sii), __float_as_uint(sii), false, false); sii = __uint_as_float(rr[0]) + __uint_as_float(rr[1]); }
;   { const unsigned* nk = nrmk + ((size_t)((b * 8 + h) * 2 + g)) * 2; const float kn = __uint_as_float(__hip_atomic_load(nk, __ATOMIC_RELAXED, __HIP_MEMORY_SCOPE_AGENT)) + __uint_as_float(__hip_atomic_load(nk + 1, __ATOMIC_RELAXED, __HIP_MEMORY_SCOPE_AGENT));
;     qn = sqrtf(qn * kn) * 1.02f - sii; }
; #pragma unroll
;   for (int x = 1; x < 32; x <<= 1) qn = fmaxf(qn, __builtin_bit_cast(float, __builtin_amdgcn_ds_bpermute((lane ^ x) << 2, __builtin_bit_cast(int, qn))));
.LBB0_358:
	s_add_u32 s11, s44, s14
	s_addc_u32 s14, s45, s15
	s_and_b64 s[0:1], exec, s[12:13]
	s_cselect_b32 s1, s14, s3
	s_cselect_b32 s0, s11, s2
	s_lshl_b32 s22, s22, 1
	s_sub_i32 s11, s16, s17
	s_sub_i32 s16, s17, s22
	s_add_i32 s23, s16, s11
	s_add_i32 s23, s23, 1
	s_not_b32 s33, s38
	s_add_i32 s39, s23, s22
	s_xor_b64 s[14:15], s[12:13], -1
	s_add_i32 s16, s38, s22
	s_add_i32 s39, s39, s33
	s_cmp_lt_i32 s38, s23
	s_cselect_b32 s16, s16, s39
	v_mov_b32_e32 v3, v1
	v_lshlrev_b32_e32 v8, 8, v7
	v_mov_b32_e32 v9, v1
	s_mov_b64 s[100:101], s[0:1]
	v_lshl_add_u64 v[10:11], s[0:1], 0, v[8:9]
	s_lshl_b32 s0, s38, 14
	s_add_i32 s0, s0, 0
	v_bitop3_b32 v12, v2, v4, s41 bitop3:0x78
	s_cmp_lt_i32 s11, 2
	v_add_u32_e32 v239, v8, v2
	v_lshl_add_u64 v[170:171], v[10:11], 0, v[2:3]
	v_add3_u32 v2, s0, v8, v12
	s_cselect_b64 s[0:1], -1, 0
	s_and_b64 s[0:1], s[14:15], s[0:1]
	s_and_b64 vcc, exec, s[0:1]
	s_waitcnt vmcnt(3)
	ds_write_b128 v2, v[146:149] offset:32768
	s_waitcnt vmcnt(2)
	ds_write_b128 v2, v[150:153] offset:36864
	s_waitcnt vmcnt(1)
	ds_write_b128 v2, v[154:157] offset:40960
	s_waitcnt vmcnt(0)
	ds_write_b128 v2, v[158:161] offset:45056
	s_cbranch_vccnz .LBB0_360
	s_and_b64 s[0:1], exec, s[12:13]
	s_cselect_b32 s0, 0, -2
	s_cselect_b32 s1, 0, 2
	s_add_i32 s0, s22, s0
	s_add_i32 s0, s0, s23
	s_add_i32 s2, s1, s22
	s_add_i32 s0, s0, -1
	s_cmp_lt_i32 s1, s23
	s_cselect_b32 s0, s2, s0
	s_lshl_b32 s0, s0, 6
	s_ashr_i32 s1, s0, 31
	s_lshl_b64 s[2:3], s[0:1], 8
	v_lshl_add_u64 v[2:3], v[170:171], 0, s[2:3]
	s_or_b32 s2, s0, 16
	s_ashr_i32 s3, s2, 31
	s_lshl_b64 s[2:3], s[2:3], 8
	v_lshl_add_u64 v[8:9], v[170:171], 0, s[2:3]
	s_or_b32 s2, s0, 32
	s_ashr_i32 s3, s2, 31
	s_or_b32 s0, s0, 48
	s_lshl_b64 s[2:3], s[2:3], 8
	s_ashr_i32 s1, s0, 31
	global_load_dwordx4 v[146:149], v[2:3], off
	global_load_dwordx4 v[150:153], v[8:9], off
	v_lshl_add_u64 v[2:3], v[170:171], 0, s[2:3]
	s_lshl_b64 s[0:1], s[0:1], 8
	v_lshl_add_u64 v[8:9], v[170:171], 0, s[0:1]
	global_load_dwordx4 v[154:157], v[2:3], off
	global_load_dwordx4 v[158:161], v[8:9], off

.LBB0_377:
	s_cmp_ge_i32 s16, s11
	s_cbranch_scc1 .LBB0_379
	s_or_b32 s16, s16, 1
	s_add_i32 s17, s16, s22
	s_sub_i32 s33, s38, s16
	s_cmp_lt_i32 s16, s23
	s_cselect_b32 s16, s17, s33
	s_lshl_b32 s16, s16, 6
	s_ashr_i32 s17, s16, 31
	s_lshl_b64 s[74:75], s[16:17], 8
	s_add_u32 s74, s74, s100
	s_addc_u32 s75, s75, s101
	s_add_u32 s74, s74, 0x1000
	s_addc_u32 s75, s75, 0
	s_add_u32 s16, s74, 0x2000
	s_addc_u32 s17, s75, 0
	global_load_dwordx4 v[146:149], v239, s[74:75] offset:-4096
	global_load_dwordx4 v[150:153], v239, s[74:75]
	global_load_dwordx4 v[154:157], v239, s[16:17] offset:-4096
	global_load_dwordx4 v[158:161], v239, s[16:17]

.LBB0_391:
	s_cmp_ge_i32 s16, s11
	s_cbranch_scc1 .LBB0_393
	s_add_i32 s17, s16, 1
	s_not_b32 s16, s16
	s_add_i32 s33, s17, s22
	s_add_i32 s16, s38, s16
	s_cmp_lt_i32 s17, s23
	s_cselect_b32 s16, s33, s16
	s_lshl_b32 s16, s16, 6
	s_ashr_i32 s17, s16, 31
	s_lshl_b64 s[72:73], s[16:17], 8
	s_add_u32 s72, s72, s100
	s_addc_u32 s73, s73, s101
	s_add_u32 s72, s72, 0x1000
	s_addc_u32 s73, s73, 0
	s_add_u32 s16, s72, 0x2000
	s_addc_u32 s17, s73, 0
	global_load_dwordx4 v[146:149], v239, s[72:73] offset:-4096
	global_load_dwordx4 v[150:153], v239, s[72:73]
	global_load_dwordx4 v[154:157], v239, s[16:17] offset:-4096
	global_load_dwordx4 v[158:161], v239, s[16:17]
